# lever8: attention prompt items with 192 keys take software-pipelined QK and PV sections (LDS fragment reads issued 6-12 ahead of their MFMAs instead of read-wait-mfma chains)
# baseline (speedup 1.0000x reference)
.LBB0_54:
	s_waitcnt lgkmcnt(0)
	s_barrier
	s_cmp_gt_u32 s39, 1
	s_cbranch_scc1 .Lqk6
	ds_read_b128 v[168:171], v231 offset:64512
	ds_read_b128 v[164:167], v231 offset:64544
	ds_read_b128 v[160:163], v231 offset:64576
	ds_read_b128 v[156:159], v231 offset:64608
	ds_read_b128 v[0:3], v232
	ds_read_b128 v[4:7], v232 offset:32
	s_waitcnt lgkmcnt(1)
	v_mfma_f32_32x32x16_bf16 v[80:95], v[0:3], v[168:171], 0
	ds_read_b128 v[0:3], v232 offset:64
	s_cmp_lg_u32 s39, 0
	s_cselect_b64 s[6:7], -1, 0
	s_cmp_eq_u32 s39, 0
	s_waitcnt lgkmcnt(1)
	v_mfma_f32_32x32x16_bf16 v[80:95], v[4:7], v[164:167], v[80:95]
	s_waitcnt lgkmcnt(0)
	v_mfma_f32_32x32x16_bf16 v[80:95], v[0:3], v[160:163], v[80:95]
	ds_read_b128 v[0:3], v232 offset:96
	s_waitcnt lgkmcnt(0)
	v_mfma_f32_32x32x16_bf16 v[80:95], v[0:3], v[156:159], v[80:95]
	ds_read_b128 v[0:3], v232 offset:4608
	s_waitcnt lgkmcnt(0)
	v_mfma_f32_32x32x16_bf16 v[64:79], v[0:3], v[168:171], 0
	ds_read_b128 v[0:3], v232 offset:4640
	s_waitcnt lgkmcnt(0)
	v_mfma_f32_32x32x16_bf16 v[64:79], v[0:3], v[164:167], v[64:79]
	ds_read_b128 v[0:3], v232 offset:4672
	s_waitcnt lgkmcnt(0)
	v_mfma_f32_32x32x16_bf16 v[64:79], v[0:3], v[160:163], v[64:79]
	ds_read_b128 v[0:3], v232 offset:4704
	s_waitcnt lgkmcnt(0)
	v_mfma_f32_32x32x16_bf16 v[64:79], v[0:3], v[156:159], v[64:79]
	s_cbranch_scc1 .LBB0_60
	ds_read_b128 v[0:3], v232 offset:9216
	s_waitcnt lgkmcnt(0)
	v_mfma_f32_32x32x16_bf16 v[48:63], v[0:3], v[168:171], 0
	ds_read_b128 v[0:3], v232 offset:9248
	s_waitcnt lgkmcnt(0)
	v_mfma_f32_32x32x16_bf16 v[48:63], v[0:3], v[164:167], v[48:63]
	ds_read_b128 v[0:3], v232 offset:9280
	s_waitcnt lgkmcnt(0)
	v_mfma_f32_32x32x16_bf16 v[48:63], v[0:3], v[160:163], v[48:63]
	ds_read_b128 v[0:3], v232 offset:9312
	s_waitcnt lgkmcnt(0)
	v_mfma_f32_32x32x16_bf16 v[48:63], v[0:3], v[156:159], v[48:63]
	s_branch .LBB0_61

.LBB0_83:
	ds_read_b64_tr_b16 v[68:69], v233 offset:27648
	ds_read_b64_tr_b16 v[70:71], v233 offset:29184
	v_cvt_pk_bf16_f32 v64, v80, v81
	v_cvt_pk_bf16_f32 v65, v82, v83
	v_cvt_pk_bf16_f32 v66, v84, v85
	v_cvt_pk_bf16_f32 v67, v86, v87
	v_cvt_pk_bf16_f32 v241, v241, v242
	v_cvt_pk_bf16_f32 v242, v243, v244
	s_waitcnt lgkmcnt(0)
	v_mfma_f32_32x32x16_bf16 v[80:95], v[68:71], v[64:67], 0
	ds_read_b64_tr_b16 v[68:69], v233 offset:27712
	ds_read_b64_tr_b16 v[70:71], v233 offset:29248
	v_cvt_pk_bf16_f32 v243, v245, v246
	ds_read_b64_tr_b16 v[244:245], v233 offset:30720
	ds_read_b64_tr_b16 v[246:247], v233 offset:32256
	v_cvt_pk_bf16_f32 v240, v239, v240
	v_cvt_pk_bf16_f32 v168, v168, v169
	v_cvt_pk_bf16_f32 v169, v170, v171
	v_cvt_pk_bf16_f32 v170, v235, v236
	s_waitcnt lgkmcnt(2)
	v_mfma_f32_32x32x16_bf16 v[64:79], v[68:71], v[64:67], 0
	v_cvt_pk_bf16_f32 v171, v237, v238
	v_cvt_pk_bf16_f32 v160, v160, v161
	v_cvt_pk_bf16_f32 v161, v162, v163
	v_cvt_pk_bf16_f32 v162, v164, v165
	v_cvt_pk_bf16_f32 v163, v166, v167
	ds_bpermute_b32 v159, v159, v158
	s_and_b64 vcc, exec, s[8:9]
	s_waitcnt lgkmcnt(1)
	v_mfma_f32_32x32x16_bf16 v[80:95], v[244:247], v[240:243], v[80:95]
	ds_read_b64_tr_b16 v[244:245], v233 offset:30784
	ds_read_b64_tr_b16 v[246:247], v233 offset:32320
	ds_read_b64_tr_b16 v[236:237], v233 offset:33792
	ds_read_b64_tr_b16 v[238:239], v233 offset:35328
	s_waitcnt lgkmcnt(2)
	v_mfma_f32_32x32x16_bf16 v[64:79], v[244:247], v[240:243], v[64:79]
	s_waitcnt lgkmcnt(0)
	v_mfma_f32_32x32x16_bf16 v[80:95], v[236:239], v[168:171], v[80:95]
	ds_read_b64_tr_b16 v[236:237], v233 offset:33856
	ds_read_b64_tr_b16 v[238:239], v233 offset:35392
	ds_read_b64_tr_b16 v[164:165], v233 offset:36864
	ds_read_b64_tr_b16 v[166:167], v233 offset:38400
	s_waitcnt lgkmcnt(2)
	v_mfma_f32_32x32x16_bf16 v[64:79], v[236:239], v[168:171], v[64:79]
	s_waitcnt lgkmcnt(0)
	v_mfma_f32_32x32x16_bf16 v[80:95], v[164:167], v[160:163], v[80:95]
	ds_read_b64_tr_b16 v[164:165], v233 offset:36928
	ds_read_b64_tr_b16 v[166:167], v233 offset:38464
	s_waitcnt lgkmcnt(0)
	v_mfma_f32_32x32x16_bf16 v[64:79], v[164:167], v[160:163], v[64:79]
	s_and_b64 vcc, exec, s[6:7]
	s_cbranch_vccz .Lpv6
	s_and_b64 vcc, exec, s[8:9]
	s_cbranch_vccnz .LBB0_85
	v_cvt_pk_bf16_f32 v48, v48, v49
	v_cvt_pk_bf16_f32 v49, v50, v51
	v_cvt_pk_bf16_f32 v50, v52, v53
	v_cvt_pk_bf16_f32 v51, v54, v55
	ds_read_b64_tr_b16 v[52:53], v233 offset:39936
	ds_read_b64_tr_b16 v[54:55], v233 offset:41472
	s_waitcnt lgkmcnt(0)
	v_mfma_f32_32x32x16_bf16 v[80:95], v[52:55], v[48:51], v[80:95]
	ds_read_b64_tr_b16 v[52:53], v233 offset:40000
	ds_read_b64_tr_b16 v[54:55], v233 offset:41536
	s_waitcnt lgkmcnt(0)
	v_mfma_f32_32x32x16_bf16 v[64:79], v[52:55], v[48:51], v[64:79]
	ds_read_b64_tr_b16 v[52:53], v233 offset:43008
	ds_read_b64_tr_b16 v[54:55], v233 offset:44544
	v_cvt_pk_bf16_f32 v48, v56, v57
	v_cvt_pk_bf16_f32 v49, v58, v59
	v_cvt_pk_bf16_f32 v50, v60, v61
	v_cvt_pk_bf16_f32 v51, v62, v63
	s_waitcnt lgkmcnt(0)
	s_nop 0
	v_mfma_f32_32x32x16_bf16 v[80:95], v[52:55], v[48:51], v[80:95]
	ds_read_b64_tr_b16 v[52:53], v233 offset:43072
	ds_read_b64_tr_b16 v[54:55], v233 offset:44608
	s_waitcnt lgkmcnt(0)
	v_mfma_f32_32x32x16_bf16 v[64:79], v[52:55], v[48:51], v[64:79]

.Lqk6:
	ds_read_b128 v[168:171], v231 offset:64512
	ds_read_b128 v[164:167], v231 offset:64544
	ds_read_b128 v[160:163], v231 offset:64576
	ds_read_b128 v[156:159], v231 offset:64608
	ds_read_b128 v[0:3], v232
	ds_read_b128 v[4:7], v232 offset:32
	ds_read_b128 v[8:11], v232 offset:64
	ds_read_b128 v[12:15], v232 offset:96
	ds_read_b128 v[16:19], v232 offset:4608
	ds_read_b128 v[20:23], v232 offset:4640
	ds_read_b128 v[24:27], v232 offset:4672
	ds_read_b128 v[28:31], v232 offset:4704
	s_waitcnt lgkmcnt(7)
	v_mfma_f32_32x32x16_bf16 v[80:95], v[0:3], v[168:171], 0
	s_waitcnt lgkmcnt(3)
	v_mfma_f32_32x32x16_bf16 v[64:79], v[16:19], v[168:171], 0
	v_mfma_f32_32x32x16_bf16 v[80:95], v[4:7], v[164:167], v[80:95]
	s_waitcnt lgkmcnt(2)
	v_mfma_f32_32x32x16_bf16 v[64:79], v[20:23], v[164:167], v[64:79]
	v_mfma_f32_32x32x16_bf16 v[80:95], v[8:11], v[160:163], v[80:95]
	s_waitcnt lgkmcnt(1)
	v_mfma_f32_32x32x16_bf16 v[64:79], v[24:27], v[160:163], v[64:79]
	v_mfma_f32_32x32x16_bf16 v[80:95], v[12:15], v[156:159], v[80:95]
	ds_read_b128 v[0:3], v232 offset:9216
	ds_read_b128 v[4:7], v232 offset:9248
	ds_read_b128 v[8:11], v232 offset:9280
	ds_read_b128 v[12:15], v232 offset:9312
	s_waitcnt lgkmcnt(4)
	v_mfma_f32_32x32x16_bf16 v[64:79], v[28:31], v[156:159], v[64:79]
	ds_read_b128 v[16:19], v232 offset:13824
	ds_read_b128 v[20:23], v232 offset:13856
	ds_read_b128 v[24:27], v232 offset:13888
	ds_read_b128 v[28:31], v232 offset:13920
	ds_read_b128 v[236:239], v232 offset:18432
	ds_read_b128 v[240:243], v232 offset:18464
	ds_read_b128 v[244:247], v232 offset:18496
	ds_read_b128 v[248:251], v232 offset:18528
	s_waitcnt lgkmcnt(11)
	v_mfma_f32_32x32x16_bf16 v[48:63], v[0:3], v[168:171], 0
	s_waitcnt lgkmcnt(7)
	v_mfma_f32_32x32x16_bf16 v[32:47], v[16:19], v[168:171], 0
	v_mfma_f32_32x32x16_bf16 v[48:63], v[4:7], v[164:167], v[48:63]
	s_waitcnt lgkmcnt(6)
	v_mfma_f32_32x32x16_bf16 v[32:47], v[20:23], v[164:167], v[32:47]
	v_mfma_f32_32x32x16_bf16 v[48:63], v[8:11], v[160:163], v[48:63]
	s_waitcnt lgkmcnt(5)
	v_mfma_f32_32x32x16_bf16 v[32:47], v[24:27], v[160:163], v[32:47]
	v_mfma_f32_32x32x16_bf16 v[48:63], v[12:15], v[156:159], v[48:63]
	ds_read_b128 v[0:3], v232 offset:23040
	ds_read_b128 v[4:7], v232 offset:23072
	ds_read_b128 v[8:11], v232 offset:23104
	ds_read_b128 v[12:15], v232 offset:23136
	s_waitcnt lgkmcnt(8)
	v_mfma_f32_32x32x16_bf16 v[32:47], v[28:31], v[156:159], v[32:47]
	s_waitcnt lgkmcnt(3)
	v_mfma_f32_32x32x16_bf16 v[16:31], v[0:3], v[168:171], 0
	s_waitcnt lgkmcnt(2)
	v_mfma_f32_32x32x16_bf16 v[16:31], v[4:7], v[164:167], v[16:31]
	s_waitcnt lgkmcnt(1)
	v_mfma_f32_32x32x16_bf16 v[16:31], v[8:11], v[160:163], v[16:31]
	s_waitcnt lgkmcnt(0)
	v_mfma_f32_32x32x16_bf16 v[16:31], v[12:15], v[156:159], v[16:31]
	v_mfma_f32_32x32x16_bf16 v[0:15], v[236:239], v[168:171], 0
	v_mfma_f32_32x32x16_bf16 v[0:15], v[240:243], v[164:167], v[0:15]
	v_mfma_f32_32x32x16_bf16 v[0:15], v[244:247], v[160:163], v[0:15]
	v_mfma_f32_32x32x16_bf16 v[0:15], v[248:251], v[156:159], v[0:15]
	s_mov_b64 s[8:9], 0
	s_mov_b64 s[6:7], 0
	s_branch .LBB0_67
.Lpv6:
	ds_read_b64_tr_b16 v[236:237], v233 offset:39936
	ds_read_b64_tr_b16 v[238:239], v233 offset:41472
	ds_read_b64_tr_b16 v[240:241], v233 offset:40000
	ds_read_b64_tr_b16 v[242:243], v233 offset:41536
	ds_read_b64_tr_b16 v[244:245], v233 offset:43008
	ds_read_b64_tr_b16 v[246:247], v233 offset:44544
	ds_read_b64_tr_b16 v[248:249], v233 offset:43072
	ds_read_b64_tr_b16 v[250:251], v233 offset:44608
	ds_read_b64_tr_b16 v[160:161], v233 offset:46080
	ds_read_b64_tr_b16 v[162:163], v233 offset:47616
	ds_read_b64_tr_b16 v[164:165], v233 offset:46144
	ds_read_b64_tr_b16 v[166:167], v233 offset:47680
	v_cvt_pk_bf16_f32 v48, v48, v49
	v_cvt_pk_bf16_f32 v49, v50, v51
	v_cvt_pk_bf16_f32 v50, v52, v53
	v_cvt_pk_bf16_f32 v51, v54, v55
	v_cvt_pk_bf16_f32 v52, v56, v57
	v_cvt_pk_bf16_f32 v53, v58, v59
	v_cvt_pk_bf16_f32 v54, v60, v61
	v_cvt_pk_bf16_f32 v55, v62, v63
	s_waitcnt lgkmcnt(10)
	v_mfma_f32_32x32x16_bf16 v[80:95], v[236:239], v[48:51], v[80:95]
	ds_read_b64_tr_b16 v[236:237], v233 offset:49152
	ds_read_b64_tr_b16 v[238:239], v233 offset:50688
	v_cvt_pk_bf16_f32 v32, v32, v33
	v_cvt_pk_bf16_f32 v33, v34, v35
	s_waitcnt lgkmcnt(10)
	v_mfma_f32_32x32x16_bf16 v[64:79], v[240:243], v[48:51], v[64:79]
	ds_read_b64_tr_b16 v[240:241], v233 offset:49216
	ds_read_b64_tr_b16 v[242:243], v233 offset:50752
	v_cvt_pk_bf16_f32 v34, v36, v37
	v_cvt_pk_bf16_f32 v35, v38, v39
	s_waitcnt lgkmcnt(10)
	v_mfma_f32_32x32x16_bf16 v[80:95], v[244:247], v[52:55], v[80:95]
	ds_read_b64_tr_b16 v[244:245], v233 offset:52224
	ds_read_b64_tr_b16 v[246:247], v233 offset:53760
	v_cvt_pk_bf16_f32 v36, v40, v41
	v_cvt_pk_bf16_f32 v37, v42, v43
	s_waitcnt lgkmcnt(10)
	v_mfma_f32_32x32x16_bf16 v[64:79], v[248:251], v[52:55], v[64:79]
	ds_read_b64_tr_b16 v[248:249], v233 offset:52288
	ds_read_b64_tr_b16 v[250:251], v233 offset:53824
	v_cvt_pk_bf16_f32 v38, v44, v45
	v_cvt_pk_bf16_f32 v39, v46, v47
	s_waitcnt lgkmcnt(10)
	v_mfma_f32_32x32x16_bf16 v[80:95], v[160:163], v[32:35], v[80:95]
	ds_read_b64_tr_b16 v[160:161], v233 offset:55296
	ds_read_b64_tr_b16 v[162:163], v233 offset:56832
	v_cvt_pk_bf16_f32 v0, v0, v1
	v_cvt_pk_bf16_f32 v1, v2, v3
	s_waitcnt lgkmcnt(10)
	v_mfma_f32_32x32x16_bf16 v[64:79], v[164:167], v[32:35], v[64:79]
	ds_read_b64_tr_b16 v[164:165], v233 offset:55360
	ds_read_b64_tr_b16 v[166:167], v233 offset:56896
	v_cvt_pk_bf16_f32 v2, v4, v5
	v_cvt_pk_bf16_f32 v3, v6, v7
	s_waitcnt lgkmcnt(10)
	v_mfma_f32_32x32x16_bf16 v[80:95], v[236:239], v[36:39], v[80:95]
	ds_read_b64_tr_b16 v[236:237], v233 offset:58368
	ds_read_b64_tr_b16 v[238:239], v233 offset:59904
	v_cvt_pk_bf16_f32 v4, v8, v9
	v_cvt_pk_bf16_f32 v5, v10, v11
	s_waitcnt lgkmcnt(10)
	v_mfma_f32_32x32x16_bf16 v[64:79], v[240:243], v[36:39], v[64:79]
	ds_read_b64_tr_b16 v[240:241], v233 offset:58432
	ds_read_b64_tr_b16 v[242:243], v233 offset:59968
	v_cvt_pk_bf16_f32 v6, v12, v13
	v_cvt_pk_bf16_f32 v7, v14, v15
	s_waitcnt lgkmcnt(10)
	v_mfma_f32_32x32x16_bf16 v[80:95], v[244:247], v[0:3], v[80:95]
	ds_read_b64_tr_b16 v[244:245], v233 offset:61440
	ds_read_b64_tr_b16 v[246:247], v233 offset:62976
	v_cvt_pk_bf16_f32 v16, v16, v17
	v_cvt_pk_bf16_f32 v17, v18, v19
	s_waitcnt lgkmcnt(10)
	v_mfma_f32_32x32x16_bf16 v[64:79], v[248:251], v[0:3], v[64:79]
	ds_read_b64_tr_b16 v[248:249], v233 offset:61504
	ds_read_b64_tr_b16 v[250:251], v233 offset:63040
	v_cvt_pk_bf16_f32 v18, v20, v21
	v_cvt_pk_bf16_f32 v19, v22, v23
	s_waitcnt lgkmcnt(10)
	v_mfma_f32_32x32x16_bf16 v[80:95], v[160:163], v[4:7], v[80:95]
	v_cvt_pk_bf16_f32 v20, v24, v25
	v_cvt_pk_bf16_f32 v21, v26, v27
	s_waitcnt lgkmcnt(8)
	v_mfma_f32_32x32x16_bf16 v[64:79], v[164:167], v[4:7], v[64:79]
	v_cvt_pk_bf16_f32 v22, v28, v29
	v_cvt_pk_bf16_f32 v23, v30, v31
	s_waitcnt lgkmcnt(6)
	v_mfma_f32_32x32x16_bf16 v[80:95], v[236:239], v[16:19], v[80:95]
	s_waitcnt lgkmcnt(4)
	v_mfma_f32_32x32x16_bf16 v[64:79], v[240:243], v[16:19], v[64:79]
	s_waitcnt lgkmcnt(2)
	v_mfma_f32_32x32x16_bf16 v[80:95], v[244:247], v[20:23], v[80:95]
	s_waitcnt lgkmcnt(0)
	v_mfma_f32_32x32x16_bf16 v[64:79], v[248:251], v[20:23], v[64:79]
	s_branch .LBB0_43
